# stack: GEMM1 row-stat prefetch, attention prologue rewrite, L2 touch prefetches (SGU su rows at item start, next mixer item lines before the attention loop)
# speedup vs baseline: 1.0072x; 1.0054x over previous
; __device__ __forceinline__ void attn_item(LAS unsigned char* lds, const bf16* P, bf16* Y, const float* qg, const float* kg, const float* sinks, int item, int tid) {
;     ...
;     { const int w_ = tid >> 6, ln = tid & 63; const bf16* qp = P + (size_t)(R0 + (w_ & 1) * 64 + (ln & 15)) * PP + (hkv * 4 + (w_ >> 1)) * 64 + 8 * (ln >> 4);
; #pragma unroll
;       for (int it = 0; it < 4; ++it) { qraw[it][0] = *(const v4u*)(qp + (size_t)(16 * it) * PP); qraw[it][1] = *(const v4u*)(qp + (size_t)(16 * it) * PP + 32); } }
; #pragma unroll
;     for (int i = 0; i < 4; ++i) {
;         const int task = tid + 512 * i, key = task >> 3, c = task & 7; const bool ok = (nb > 0) || (key >= 128);
;         v4u kr = {0u, 0u, 0u, 0u}, vr = {0u, 0u, 0u, 0u};
;         if (ok) { const bf16* rp = P + (size_t)(R0 - 128 + key) * PP + hkv * 64 + 8 * c; kr = *(const v4u*)(rp + C_K); vr = *(const v4u*)(rp + C_V); }
.LBB0_132:
	s_andn2_b64 vcc, exec, s[18:19]
	s_cbranch_vccnz .LBB0_129
	s_bfe_u32 s3, s25, 0x40001
	s_lshl_b32 s22, s25, 6
	s_and_b32 s18, s22, 0xfffff800
	s_lshl_b32 s19, s3, 7
	s_and_b32 s2, s25, 1
	s_or_b32 s23, s19, s18
	v_or_b32_e32 v3, s23, v191
	v_mov_b64_e32 v[0:1], s[16:17]
	v_lshl_add_u32 v46, s2, 2, v192
	v_mad_i64_i32 v[4:5], s[18:19], v3, s36, v[0:1]
	v_lshlrev_b32_e32 v0, 6, v46
	v_ashrrev_i32_e32 v1, 31, v0
	v_lshl_add_u64 v[4:5], v[0:1], 1, v[4:5]
	v_mov_b32_e32 v123, v2
	v_lshl_add_u64 v[20:21], v[4:5], 0, v[122:123]
	global_load_dwordx4 v[160:163], v[104:105], off offset:16
	global_load_dwordx4 v[164:167], v[104:105], off
	v_ashrrev_i32_e32 v47, 31, v46
	v_lshl_add_u64 v[36:37], v[46:47], 2, s[42:43]
	global_load_dword v184, v[36:37], off
	global_load_dwordx4 v[168:171], v[108:109], off
	global_load_dwordx4 v[172:175], v[108:109], off offset:16
	global_load_dwordx4 v[176:179], v[108:109], off offset:128
	global_load_dwordx4 v[180:183], v[108:109], off offset:144
	s_mov_b32 s18, 0x17000
	v_add_co_u32_e32 v8, vcc, s18, v20
	s_mov_b32 s18, 0x2e000
	s_nop 0
	v_addc_co_u32_e32 v9, vcc, 0, v21, vcc
	v_add_co_u32_e32 v16, vcc, s18, v20
	s_mov_b32 s18, 0x45000
	s_nop 0
	v_addc_co_u32_e32 v17, vcc, 0, v21, vcc
	v_add_co_u32_e32 v24, vcc, s18, v20
	global_load_dwordx4 v[32:35], v[20:21], off
	global_load_dwordx4 v[28:31], v[20:21], off offset:64
	v_addc_co_u32_e32 v25, vcc, 0, v21, vcc
	global_load_dwordx4 v[4:7], v[8:9], off
	s_nop 0
	global_load_dwordx4 v[8:11], v[8:9], off offset:64
	s_nop 0
	global_load_dwordx4 v[12:15], v[16:17], off
	s_nop 0
	global_load_dwordx4 v[16:19], v[16:17], off offset:64
	s_nop 0
	global_load_dwordx4 v[20:23], v[24:25], off
	s_nop 0
	global_load_dwordx4 v[24:27], v[24:25], off offset:64
	v_readlane_b32 s18, v254, 31
	s_cmp_lg_u32 s3, 0
	v_readlane_b32 s19, v254, 32
	s_cselect_b64 s[44:45], -1, 0
	s_mov_b32 s29, s19
	s_lshl_b32 s28, s2, 7
	v_writelane_b32 v254, s18, 31
	s_addk_i32 s23, 0xff80
	v_lshl_add_u64 v[48:49], v[106:107], 0, s[28:29]
	v_writelane_b32 v254, s19, 32
	s_or_b64 s[28:29], s[64:65], s[44:45]
	v_mov_b32_e32 v64, 0
	v_mov_b32_e32 v65, 0
	v_mov_b32_e32 v66, 0
	v_mov_b32_e32 v67, 0
	v_mov_b32_e32 v68, 0
	v_mov_b32_e32 v69, 0
	v_mov_b32_e32 v70, 0
	v_mov_b32_e32 v71, 0
	v_mov_b32_e32 v76, 0
	v_mov_b32_e32 v77, 0
	v_mov_b32_e32 v78, 0
	v_mov_b32_e32 v79, 0
	v_mov_b32_e32 v80, 0
	v_mov_b32_e32 v81, 0
	v_mov_b32_e32 v82, 0
	v_mov_b32_e32 v83, 0
	v_mov_b32_e32 v84, 0
	v_mov_b32_e32 v85, 0
	v_mov_b32_e32 v86, 0
	v_mov_b32_e32 v87, 0
	v_mov_b32_e32 v88, 0
	v_mov_b32_e32 v89, 0
	v_mov_b32_e32 v90, 0
	v_mov_b32_e32 v91, 0
	v_mov_b32_e32 v92, 0
	v_mov_b32_e32 v93, 0
	v_mov_b32_e32 v94, 0
	v_mov_b32_e32 v95, 0
	v_mov_b32_e32 v96, 0
	v_mov_b32_e32 v97, 0
	v_mov_b32_e32 v98, 0
	v_mov_b32_e32 v99, 0
	s_or_b64 s[28:29], s[44:45], s[64:65]
	v_add_u32_e32 v37, s23, v193
	v_mad_i64_i32 v[38:39], s[18:19], v37, s36, v[48:49]
	s_and_saveexec_b64 s[34:35], s[28:29]
	global_load_dwordx4 v[64:67], v[38:39], off offset:1024
	global_load_dwordx4 v[68:71], v[38:39], off offset:1280
	s_or_b64 exec, exec, s[34:35]
	s_or_b64 s[28:29], s[44:45], s[84:85]
	v_add_u32_e32 v37, s23, v195
	v_mad_i64_i32 v[40:41], s[18:19], v37, s36, v[48:49]
	s_and_saveexec_b64 s[34:35], s[28:29]
	global_load_dwordx4 v[76:79], v[40:41], off offset:1024
	global_load_dwordx4 v[80:83], v[40:41], off offset:1280
	s_or_b64 exec, exec, s[34:35]
	s_or_b64 s[28:29], s[44:45], s[90:91]
	v_add_u32_e32 v37, s23, v203
	v_mad_i64_i32 v[42:43], s[18:19], v37, s36, v[48:49]
	s_and_saveexec_b64 s[34:35], s[28:29]
	global_load_dwordx4 v[84:87], v[42:43], off offset:1024
	global_load_dwordx4 v[88:91], v[42:43], off offset:1280
	s_or_b64 exec, exec, s[34:35]
	s_or_b64 s[28:29], s[44:45], s[92:93]
	v_add_u32_e32 v37, s23, v205
	v_mad_i64_i32 v[44:45], s[18:19], v37, s36, v[48:49]
	s_and_saveexec_b64 s[34:35], s[28:29]
	global_load_dwordx4 v[92:95], v[44:45], off offset:1024
	global_load_dwordx4 v[96:99], v[44:45], off offset:1280
	s_or_b64 exec, exec, s[34:35]
	v_and_b32_e32 v3, 64, v235
	v_add_u32_e32 v3, 64, v3
	v_xor_b32_e32 v37, 1, v235
	v_cmp_lt_i32_e32 vcc, v37, v3
	s_nop 1
	v_cndmask_b32_e32 v37, v235, v37, vcc
	v_lshlrev_b32_e32 v47, 2, v37
	v_xor_b32_e32 v37, 2, v235
	v_cmp_lt_i32_e32 vcc, v37, v3
	s_nop 1
	v_cndmask_b32_e32 v37, v235, v37, vcc
	v_lshlrev_b32_e32 v50, 2, v37
	v_xor_b32_e32 v37, 4, v235
	v_cmp_lt_i32_e32 vcc, v37, v3
	s_nop 1
	v_cndmask_b32_e32 v37, v235, v37, vcc
	v_lshlrev_b32_e32 v51, 2, v37
	s_waitcnt vmcnt(6)
	v_lshlrev_b32_e32 v56, 16, v64
	v_and_b32_e32 v57, 0xffff0000, v64
	v_lshlrev_b32_e32 v59, 16, v65
	v_and_b32_e32 v58, 0xffff0000, v65
	v_lshlrev_b32_e32 v61, 16, v66
	v_and_b32_e32 v60, 0xffff0000, v66
	v_lshlrev_b32_e32 v63, 16, v67
	v_and_b32_e32 v62, 0xffff0000, v67
	v_mul_f32_e32 v52, v56, v56
	v_mul_f32_e32 v37, v57, v57
	v_add_f32_e32 v52, v52, v37
	v_mul_f32_e32 v37, v59, v59
	v_add_f32_e32 v52, v37, v52
	v_mul_f32_e32 v37, v58, v58
	v_add_f32_e32 v52, v37, v52
	v_mul_f32_e32 v37, v61, v61
	v_add_f32_e32 v52, v37, v52
	v_mul_f32_e32 v37, v60, v60
	v_add_f32_e32 v52, v37, v52
	v_mul_f32_e32 v37, v63, v63
	v_add_f32_e32 v52, v37, v52
	v_mul_f32_e32 v37, v62, v62
	v_add_f32_e32 v52, v37, v52
	s_waitcnt vmcnt(4)
	v_lshlrev_b32_e32 v56, 16, v76
	v_and_b32_e32 v57, 0xffff0000, v76
	v_lshlrev_b32_e32 v59, 16, v77
	v_and_b32_e32 v58, 0xffff0000, v77
	v_lshlrev_b32_e32 v61, 16, v78
	v_and_b32_e32 v60, 0xffff0000, v78
	v_lshlrev_b32_e32 v63, 16, v79
	v_and_b32_e32 v62, 0xffff0000, v79
	v_mul_f32_e32 v53, v56, v56
	v_mul_f32_e32 v37, v57, v57
	v_add_f32_e32 v53, v53, v37
	v_mul_f32_e32 v37, v59, v59
	v_add_f32_e32 v53, v37, v53
	v_mul_f32_e32 v37, v58, v58
	v_add_f32_e32 v53, v37, v53
	v_mul_f32_e32 v37, v61, v61
	v_add_f32_e32 v53, v37, v53
	v_mul_f32_e32 v37, v60, v60
	v_add_f32_e32 v53, v37, v53
	v_mul_f32_e32 v37, v63, v63
	v_add_f32_e32 v53, v37, v53
	v_mul_f32_e32 v37, v62, v62
	v_add_f32_e32 v53, v37, v53
	s_waitcnt vmcnt(2)
; __device__ __forceinline__ unsigned cvt_pk_bf16(float lo, float hi) { unsigned r; asm volatile("v_cvt_pk_bf16_f32 %0, %1, %2" : "=v"(r) : "v"(lo), "v"(hi)); return r; }
; __device__ __forceinline__ float bflo(unsigned u) { return __uint_as_float(u << 16); }
; __device__ __forceinline__ float bfhi(unsigned u) { return __uint_as_float(u & 0xffff0000u); }
; #define LAS __attribute__((address_space(3)))
; __device__ __forceinline__ void attn_item(LAS unsigned char* lds, const bf16* P, bf16* Y, const float* qg, const float* kg, const float* sinks, int item, int tid) {
;     ...
;         float kf[8];
; #pragma unroll
;         for (int e = 0; e < 4; ++e) { kf[2 * e] = bflo(kr[e]); kf[2 * e + 1] = bfhi(kr[e]); }
;         float ss = 0.f;
; #pragma unroll
;         for (int e = 0; e < 8; ++e) ss += kf[e] * kf[e];
;         ss += __shfl_xor(ss, 1); ss += __shfl_xor(ss, 2); ss += __shfl_xor(ss, 4);
;         const float rs = rsqrtf(ss * (1.f / 64.f) + EPS);
;         const f32x4 g0 = *(const f32x4*)(kg + 8 * c), g1 = *(const f32x4*)(kg + 8 * c + 4);
;         v4u kw; kw.x = cvt_pk_bf16(kf[0] * rs * g0.x, kf[1] * rs * g0.y); kw.y = cvt_pk_bf16(kf[2] * rs * g0.z, kf[3] * rs * g0.w);
;         kw.z = cvt_pk_bf16(kf[4] * rs * g1.x, kf[5] * rs * g1.y); kw.w = cvt_pk_bf16(kf[6] * rs * g1.z, kf[7] * rs * g1.w);
;         *(LAS v4u*)(Ks + key * 72 + 8 * c) = kw;
; #pragma unroll
;         for (int e = 0; e < 4; ++e) { Vt[(8 * c + 2 * e) * 264 + key] = (bf16)(vr[e] & 0xffffu); Vt[(8 * c + 2 * e + 1) * 264 + key] = (bf16)(vr[e] >> 16); }
	v_lshlrev_b32_e32 v56, 16, v84
	v_and_b32_e32 v57, 0xffff0000, v84
	v_lshlrev_b32_e32 v59, 16, v85
	v_and_b32_e32 v58, 0xffff0000, v85
	v_lshlrev_b32_e32 v61, 16, v86
	v_and_b32_e32 v60, 0xffff0000, v86
	v_lshlrev_b32_e32 v63, 16, v87
	v_and_b32_e32 v62, 0xffff0000, v87
	v_mul_f32_e32 v54, v56, v56
	v_mul_f32_e32 v37, v57, v57
	v_add_f32_e32 v54, v54, v37
	v_mul_f32_e32 v37, v59, v59
	v_add_f32_e32 v54, v37, v54
	v_mul_f32_e32 v37, v58, v58
	v_add_f32_e32 v54, v37, v54
	v_mul_f32_e32 v37, v61, v61
	v_add_f32_e32 v54, v37, v54
	v_mul_f32_e32 v37, v60, v60
	v_add_f32_e32 v54, v37, v54
	v_mul_f32_e32 v37, v63, v63
	v_add_f32_e32 v54, v37, v54
	v_mul_f32_e32 v37, v62, v62
	v_add_f32_e32 v54, v37, v54
	s_waitcnt vmcnt(0)
	v_lshlrev_b32_e32 v56, 16, v92
	v_and_b32_e32 v57, 0xffff0000, v92
	v_lshlrev_b32_e32 v59, 16, v93
	v_and_b32_e32 v58, 0xffff0000, v93
	v_lshlrev_b32_e32 v61, 16, v94
	v_and_b32_e32 v60, 0xffff0000, v94
	v_lshlrev_b32_e32 v63, 16, v95
	v_and_b32_e32 v62, 0xffff0000, v95
	v_mul_f32_e32 v55, v56, v56
	v_mul_f32_e32 v37, v57, v57
	v_add_f32_e32 v55, v55, v37
	v_mul_f32_e32 v37, v59, v59
	v_add_f32_e32 v55, v37, v55
	v_mul_f32_e32 v37, v58, v58
	v_add_f32_e32 v55, v37, v55
	v_mul_f32_e32 v37, v61, v61
	v_add_f32_e32 v55, v37, v55
	v_mul_f32_e32 v37, v60, v60
	v_add_f32_e32 v55, v37, v55
	v_mul_f32_e32 v37, v63, v63
	v_add_f32_e32 v55, v37, v55
	v_mul_f32_e32 v37, v62, v62
	v_add_f32_e32 v55, v37, v55
	ds_bpermute_b32 v40, v47, v52
	ds_bpermute_b32 v41, v47, v53
	ds_bpermute_b32 v42, v47, v54
	ds_bpermute_b32 v43, v47, v55
	s_waitcnt lgkmcnt(0)
	v_add_f32_e32 v52, v52, v40
	v_add_f32_e32 v53, v53, v41
	v_add_f32_e32 v54, v54, v42
	v_add_f32_e32 v55, v55, v43
	ds_bpermute_b32 v40, v50, v52
	ds_bpermute_b32 v41, v50, v53
	ds_bpermute_b32 v42, v50, v54
	ds_bpermute_b32 v43, v50, v55
	s_waitcnt lgkmcnt(0)
	v_add_f32_e32 v52, v52, v40
	v_add_f32_e32 v53, v53, v41
	v_add_f32_e32 v54, v54, v42
	v_add_f32_e32 v55, v55, v43
	ds_bpermute_b32 v40, v51, v52
	ds_bpermute_b32 v41, v51, v53
	ds_bpermute_b32 v42, v51, v54
	ds_bpermute_b32 v43, v51, v55
	s_waitcnt lgkmcnt(0)
	v_add_f32_e32 v52, v52, v40
	v_add_f32_e32 v53, v53, v41
	v_add_f32_e32 v54, v54, v42
	v_add_f32_e32 v55, v55, v43
	v_fmamk_f32 v52, v52, 0x3c800000, v196
	v_cmp_gt_f32_e32 vcc, s13, v52
	v_mul_f32_e32 v37, 0x4b800000, v52
	s_nop 0
	v_cndmask_b32_e32 v52, v52, v37, vcc
	v_rsq_f32_e32 v52, v52
	s_nop 0
	v_mul_f32_e32 v37, 0x45800000, v52
	v_cndmask_b32_e32 v52, v52, v37, vcc
	v_fmamk_f32 v53, v53, 0x3c800000, v196
	v_cmp_gt_f32_e32 vcc, s13, v53
	v_mul_f32_e32 v37, 0x4b800000, v53
	s_nop 0
	v_cndmask_b32_e32 v53, v53, v37, vcc
	v_rsq_f32_e32 v53, v53
	s_nop 0
	v_mul_f32_e32 v37, 0x45800000, v53
	v_cndmask_b32_e32 v53, v53, v37, vcc
	v_fmamk_f32 v54, v54, 0x3c800000, v196
	v_cmp_gt_f32_e32 vcc, s13, v54
	v_mul_f32_e32 v37, 0x4b800000, v54
	s_nop 0
	v_cndmask_b32_e32 v54, v54, v37, vcc
	v_rsq_f32_e32 v54, v54
	s_nop 0
	v_mul_f32_e32 v37, 0x45800000, v54
	v_cndmask_b32_e32 v54, v54, v37, vcc
	v_fmamk_f32 v55, v55, 0x3c800000, v196
	v_cmp_gt_f32_e32 vcc, s13, v55
	v_mul_f32_e32 v37, 0x4b800000, v55
	s_nop 0
	v_cndmask_b32_e32 v55, v55, v37, vcc
	v_rsq_f32_e32 v55, v55
	s_nop 0
	v_mul_f32_e32 v37, 0x45800000, v55
	v_cndmask_b32_e32 v55, v55, v37, vcc
	v_lshlrev_b32_e32 v56, 16, v64
	v_and_b32_e32 v57, 0xffff0000, v64
	v_lshlrev_b32_e32 v59, 16, v65
	v_and_b32_e32 v58, 0xffff0000, v65
	v_lshlrev_b32_e32 v61, 16, v66
	v_and_b32_e32 v60, 0xffff0000, v66
	v_lshlrev_b32_e32 v63, 16, v67
	v_and_b32_e32 v62, 0xffff0000, v67
	v_mul_f32_e32 v56, v52, v56
	v_mul_f32_e32 v56, v164, v56
	v_mul_f32_e32 v57, v52, v57
	v_mul_f32_e32 v57, v165, v57
	v_mul_f32_e32 v59, v52, v59
	v_mul_f32_e32 v59, v166, v59
	v_mul_f32_e32 v58, v52, v58
	v_mul_f32_e32 v58, v167, v58
	v_mul_f32_e32 v61, v52, v61
	v_mul_f32_e32 v61, v160, v61
	v_mul_f32_e32 v60, v52, v60
	v_mul_f32_e32 v60, v161, v60
	v_mul_f32_e32 v63, v52, v63
	v_mul_f32_e32 v63, v162, v63
	v_mul_f32_e32 v62, v52, v62
	v_mul_f32_e32 v62, v163, v62
	v_cvt_pk_bf16_f32 v40, v56, v57
	v_cvt_pk_bf16_f32 v41, v59, v58
	v_cvt_pk_bf16_f32 v42, v61, v60
	v_cvt_pk_bf16_f32 v43, v63, v62
	ds_write_b128 v219, v[40:43]
	ds_write_b16 v194, v68 offset:36864
	ds_write_b16_d16_hi v194, v68 offset:37392
	ds_write_b16 v194, v69 offset:37920
	ds_write_b16_d16_hi v194, v69 offset:38448
	ds_write_b16 v194, v70 offset:38976
	ds_write_b16_d16_hi v194, v70 offset:39504
	ds_write_b16 v194, v71 offset:40032
	ds_write_b16_d16_hi v194, v71 offset:40560
	v_lshlrev_b32_e32 v56, 16, v76
	v_and_b32_e32 v57, 0xffff0000, v76
	v_lshlrev_b32_e32 v59, 16, v77
	v_and_b32_e32 v58, 0xffff0000, v77
	v_lshlrev_b32_e32 v61, 16, v78
	v_and_b32_e32 v60, 0xffff0000, v78
	v_lshlrev_b32_e32 v63, 16, v79
	v_and_b32_e32 v62, 0xffff0000, v79
	v_mul_f32_e32 v56, v53, v56
	v_mul_f32_e32 v56, v164, v56
	v_mul_f32_e32 v57, v53, v57
	v_mul_f32_e32 v57, v165, v57
	v_mul_f32_e32 v59, v53, v59
	v_mul_f32_e32 v59, v166, v59
	v_mul_f32_e32 v58, v53, v58
	v_mul_f32_e32 v58, v167, v58
	v_mul_f32_e32 v61, v53, v61
	v_mul_f32_e32 v61, v160, v61
	v_mul_f32_e32 v60, v53, v60
	v_mul_f32_e32 v60, v161, v60
	v_mul_f32_e32 v63, v53, v63
	v_mul_f32_e32 v63, v162, v63
	v_mul_f32_e32 v62, v53, v62
	v_mul_f32_e32 v62, v163, v62
	v_cvt_pk_bf16_f32 v40, v56, v57
	v_cvt_pk_bf16_f32 v41, v59, v58
	v_cvt_pk_bf16_f32 v42, v61, v60
	v_cvt_pk_bf16_f32 v43, v63, v62
	ds_write_b128 v220, v[40:43]
	ds_write_b16 v202, v80 offset:36864
	ds_write_b16_d16_hi v202, v80 offset:37392
	ds_write_b16 v202, v81 offset:37920
	ds_write_b16_d16_hi v202, v81 offset:38448
	ds_write_b16 v202, v82 offset:38976
	ds_write_b16_d16_hi v202, v82 offset:39504
; #define LAS __attribute__((address_space(3)))
; __device__ __forceinline__ void attn_item(LAS unsigned char* lds, const bf16* P, bf16* Y, const float* qg, const float* kg, const float* sinks, int item, int tid) {
;     ...
;         *(LAS v4u*)(Ks + key * 72 + 8 * c) = kw;
; #pragma unroll
;         for (int e = 0; e < 4; ++e) { Vt[(8 * c + 2 * e) * 264 + key] = (bf16)(vr[e] & 0xffffu); Vt[(8 * c + 2 * e + 1) * 264 + key] = (bf16)(vr[e] >> 16); }
;     }
;     __syncthreads();
;     const int w = tid >> 6, lane = tid & 63, fr = lane & 15, fq = lane >> 4, g = w >> 1, h = hkv * 4 + g, half = w & 1;
;     const float slope2 = exp2f(-(float)(h + 1)) * LOG2E, sink2 = sinks[h] * LOG2E;
;     f32x4 qgv[4];
; #pragma unroll
;     for (int ks = 0; ks < 2; ++ks) { qgv[2 * ks] = *(const f32x4*)(qg + 32 * ks + 8 * fq); qgv[2 * ks + 1] = *(const f32x4*)(qg + 32 * ks + 8 * fq + 4); }
;     const int d0i = fr + 128 - 4 * fq; const float t0 = -slope2 * (float)d0i;
;     float be[2][4];
; #pragma unroll
;     for (int r = 0; r < 4; ++r) { const int da = d0i - r, db8 = d0i - 128 - r; be[0][r] = (da < 128) ? -slope2 * (float)da : -1e30f; be[1][r] = (db8 >= 0) ? -slope2 * (float)db8 : -1e30f; }
; __global__ void __launch_bounds__(NWAVES * 64, 2) fwd_kernel(Args args) {
;     ...
;                 for (int it = bid; it < 768; it += G) {
;                     if (it < 512) attn_item(lds, Pb, Yb, a.in[3] + l * 64, a.in[4] + l * 64, a.in[5] + l * 8, it, tid);
	ds_write_b16 v202, v83 offset:40032
	ds_write_b16_d16_hi v202, v83 offset:40560
	v_lshlrev_b32_e32 v56, 16, v84
	v_and_b32_e32 v57, 0xffff0000, v84
	v_lshlrev_b32_e32 v59, 16, v85
	v_and_b32_e32 v58, 0xffff0000, v85
	v_lshlrev_b32_e32 v61, 16, v86
	v_and_b32_e32 v60, 0xffff0000, v86
	v_lshlrev_b32_e32 v63, 16, v87
	v_and_b32_e32 v62, 0xffff0000, v87
	v_mul_f32_e32 v56, v54, v56
	v_mul_f32_e32 v56, v164, v56
	v_mul_f32_e32 v57, v54, v57
	v_mul_f32_e32 v57, v165, v57
	v_mul_f32_e32 v59, v54, v59
	v_mul_f32_e32 v59, v166, v59
	v_mul_f32_e32 v58, v54, v58
	v_mul_f32_e32 v58, v167, v58
	v_mul_f32_e32 v61, v54, v61
	v_mul_f32_e32 v61, v160, v61
	v_mul_f32_e32 v60, v54, v60
	v_mul_f32_e32 v60, v161, v60
	v_mul_f32_e32 v63, v54, v63
	v_mul_f32_e32 v63, v162, v63
	v_mul_f32_e32 v62, v54, v62
	v_mul_f32_e32 v62, v163, v62
	v_cvt_pk_bf16_f32 v40, v56, v57
	v_cvt_pk_bf16_f32 v41, v59, v58
	v_cvt_pk_bf16_f32 v42, v61, v60
	v_cvt_pk_bf16_f32 v43, v63, v62
	ds_write_b128 v221, v[40:43]
	ds_write_b16 v204, v88 offset:36864
	ds_write_b16_d16_hi v204, v88 offset:37392
	ds_write_b16 v204, v89 offset:37920
	ds_write_b16_d16_hi v204, v89 offset:38448
	ds_write_b16 v204, v90 offset:38976
	ds_write_b16_d16_hi v204, v90 offset:39504
	ds_write_b16 v204, v91 offset:40032
	ds_write_b16_d16_hi v204, v91 offset:40560
	v_lshlrev_b32_e32 v56, 16, v92
	v_and_b32_e32 v57, 0xffff0000, v92
	v_lshlrev_b32_e32 v59, 16, v93
	v_and_b32_e32 v58, 0xffff0000, v93
	v_lshlrev_b32_e32 v61, 16, v94
	v_and_b32_e32 v60, 0xffff0000, v94
	v_lshlrev_b32_e32 v63, 16, v95
	v_and_b32_e32 v62, 0xffff0000, v95
	v_mul_f32_e32 v56, v55, v56
	v_mul_f32_e32 v56, v164, v56
	v_mul_f32_e32 v57, v55, v57
	v_mul_f32_e32 v57, v165, v57
	v_mul_f32_e32 v59, v55, v59
	v_mul_f32_e32 v59, v166, v59
	v_mul_f32_e32 v58, v55, v58
	v_mul_f32_e32 v58, v167, v58
	v_mul_f32_e32 v61, v55, v61
	v_mul_f32_e32 v61, v160, v61
	v_mul_f32_e32 v60, v55, v60
	v_mul_f32_e32 v60, v161, v60
	v_mul_f32_e32 v63, v55, v63
	v_mul_f32_e32 v63, v162, v63
	v_mul_f32_e32 v62, v55, v62
	v_mul_f32_e32 v62, v163, v62
	v_cvt_pk_bf16_f32 v40, v56, v57
	v_cvt_pk_bf16_f32 v41, v59, v58
	v_cvt_pk_bf16_f32 v42, v61, v60
	v_cvt_pk_bf16_f32 v43, v63, v62
	ds_write_b128 v222, v[40:43]
	ds_write_b16 v206, v96 offset:36864
	ds_write_b16_d16_hi v206, v96 offset:37392
	ds_write_b16 v206, v97 offset:37920
	ds_write_b16_d16_hi v206, v97 offset:38448
	ds_write_b16 v206, v98 offset:38976
	ds_write_b16_d16_hi v206, v98 offset:39504
	ds_write_b16 v206, v99 offset:40032
	ds_write_b16_d16_hi v206, v99 offset:40560
	s_and_b32 s18, s24, 0xfffff800
	v_or_b32_e32 v44, s18, v191
	s_and_b32 s18, s22, 0x780
	v_or_b32_e32 v72, s18, v44
	s_mov_b32 s2, 0
	s_mov_b32 s18, 0x42fc0000
	s_cmp_eq_u32 s3, 0
	s_cselect_b64 s[62:63], -1, 0
	v_lshl_add_u64 v[74:75], v[0:1], 1, v[110:111]
	v_mov_b32_e32 v0, v218
	v_mov_b32_e32 v133, v215
	v_add_u32_e32 v36, 1, v46
	v_cvt_f32_i32_e32 v36, v36
	v_mov_b32_e32 v37, 0x42800000
	v_ashrrev_i32_e32 v47, 31, v46
	v_cmp_lt_f32_e32 vcc, s18, v36
	s_waitcnt lgkmcnt(0)
	s_barrier
	v_cndmask_b32_e32 v37, 0, v37, vcc
	v_sub_f32_e32 v36, v37, v36
	v_exp_f32_e32 v36, v36
	v_not_b32_e32 v37, 63
	v_cndmask_b32_e32 v37, 0, v37, vcc
	v_ldexp_f32 v52, v36, v37
	v_mov_b32_e32 v53, v184
	v_mov_b32_e32 v36, v168
	v_mov_b32_e32 v37, v169
	v_mov_b32_e32 v38, v170
	v_mov_b32_e32 v39, v171
	v_mov_b32_e32 v40, v172
	v_mov_b32_e32 v41, v173
	v_mov_b32_e32 v42, v174
	v_mov_b32_e32 v43, v175
	v_mov_b32_e32 v44, v176
	v_mov_b32_e32 v45, v177
	v_mov_b32_e32 v46, v178
	v_mov_b32_e32 v47, v179
	v_mov_b32_e32 v48, v180
	v_mov_b32_e32 v49, v181
	v_mov_b32_e32 v50, v182
	v_mov_b32_e32 v51, v183
	s_add_i32 s18, s25, s12
	s_cmpk_gt_i32 s18, 0x2ff
	s_cbranch_scc1 .Lpf_done
	s_cmpk_gt_i32 s18, 0x1ff
	s_cbranch_scc1 .Lpf_sgu
	s_lshl_b32 s19, s18, 6
	s_and_b32 s28, s19, 0xfffff800
	s_bfe_u32 s29, s18, 0x40001
	s_lshl_b32 s29, s29, 7
	s_or_b32 s28, s28, s29
	s_and_b32 s29, s18, 1
	v_lshrrev_b32_e32 v164, 2, v242
	v_add_u32_e32 v164, s28, v164
	v_mul_lo_u32 v164, v164, s36
	v_and_b32_e32 v165, 3, v242
	v_lshlrev_b32_e32 v165, 7, v165
	s_lshl_b32 s19, s29, 9
	v_add3_u32 v164, v164, v165, s19
	v_mov_b32_e32 v165, 0
	v_lshl_add_u64 v[166:167], v[164:165], 0, s[16:17]
	global_load_dword v160, v[166:167], off
	v_lshrrev_b32_e32 v164, 1, v242
	v_add_u32_e32 v164, s28, v164
	v_subrev_u32_e32 v164, 0x80, v164
	v_max_i32_e32 v164, 0, v164
	v_mul_lo_u32 v164, v164, s36
	v_and_b32_e32 v165, 1, v242
	v_lshlrev_b32_e32 v165, 8, v165
	s_lshl_b32 s19, s29, 7
	s_addk_i32 s19, 0x400
	v_add3_u32 v164, v164, v165, s19
	v_mov_b32_e32 v165, 0
	v_lshl_add_u64 v[166:167], v[164:165], 0, s[16:17]
	global_load_dword v161, v[166:167], off
	s_branch .Lpf_done
; __device__ __forceinline__ void attn_item(LAS unsigned char* lds, const bf16* P, bf16* Y, const float* qg, const float* kg, const float* sinks, int item, int tid) {
;     ...
;     const float slope2 = exp2f(-(float)(h + 1)) * LOG2E, sink2 = sinks[h] * LOG2E;
;     f32x4 qgv[4];
; #pragma unroll
;     for (int ks = 0; ks < 2; ++ks) { qgv[2 * ks] = *(const f32x4*)(qg + 32 * ks + 8 * fq); qgv[2 * ks + 1] = *(const f32x4*)(qg + 32 * ks + 8 * fq + 4); }
;     const int d0i = fr + 128 - 4 * fq; const float t0 = -slope2 * (float)d0i;
;     float be[2][4];
; #pragma unroll
;     for (int r = 0; r < 4; ++r) { const int da = d0i - r, db8 = d0i - 128 - r; be[0][r] = (da < 128) ? -slope2 * (float)da : -1e30f; be[1][r] = (db8 >= 0) ? -slope2 * (float)db8 : -1e30f; }
;     ...
;         float mx = sink2;
; #pragma unroll
;         for (int k9 = 0; k9 < 9; ++k9) { const bool nokey = (nb == 0) && (qb + k9 < 8);
; #pragma unroll
;             for (int r = 0; r < 4; ++r) {
;                 float s = (k9 == 0) ? sc[k9][r] + be[0][r] : (k9 == 8) ? sc[k9][r] + be[1][r] : sc[k9][r] + __builtin_fmaf(slope2, (float)(16 * k9 + r), t0);
;                 s = nokey ? -1e30f : s; sc[k9][r] = s; mx = fmaxf(mx, s); } }
;         mx = fmaxf(mx, __shfl_xor(mx, 16)); mx = fmaxf(mx, __shfl_xor(mx, 32));
.Lpf_sgu:
	s_lshl_b32 s28, s18, 7
	s_add_i32 s28, s28, 0xffff0000
	v_lshrrev_b32_e32 v164, 2, v242
	v_add_u32_e32 v164, s28, v164
	v_mul_lo_u32 v164, v164, s36
	v_and_b32_e32 v165, 3, v242
	v_lshlrev_b32_e32 v165, 8, v165
	v_add_u32_e32 v164, v164, v165
	v_mov_b32_e32 v165, 0
	v_lshl_add_u64 v[166:167], v[164:165], 0, s[16:17]
	global_load_dword v160, v[166:167], off offset:2560
	global_load_dword v161, v[166:167], off offset:2688
.Lpf_done:
	v_mul_f32_e32 v52, 0xbfb8aa3b, v52
	v_mul_f32_e32 v54, v208, v52
	v_cndmask_b32_e64 v78, v236, v54, s[48:49]
	v_mul_f32_e32 v54, v209, v52
	v_cndmask_b32_e64 v79, v236, v54, s[50:51]
	v_mul_f32_e32 v54, v210, v52
	v_cndmask_b32_e64 v80, v236, v54, s[52:53]
	v_mul_f32_e32 v54, v211, v52
	v_cndmask_b32_e64 v81, v236, v54, s[54:55]
	v_mul_f32_e32 v54, v212, v52
	v_cndmask_b32_e64 v82, v236, v54, s[56:57]
	v_mul_f32_e32 v54, v213, v52
	v_mul_f32_e32 v76, v207, v52
	v_cndmask_b32_e64 v83, v236, v54, s[58:59]
	v_mul_f32_e32 v54, v214, v52
	v_cndmask_b32_e64 v77, v236, v76, s[46:47]
	v_cndmask_b32_e64 v84, v236, v54, s[60:61]
	v_fmamk_f32 v88, v52, 0xc1800000, v76
	v_fmamk_f32 v89, v52, 0xc1880000, v76
	v_fmamk_f32 v90, v52, 0xc1900000, v76
	v_fmamk_f32 v91, v52, 0xc1980000, v76
	v_fmamk_f32 v92, v52, 0xc2000000, v76
	v_fmamk_f32 v93, v52, 0xc2040000, v76
	v_fmamk_f32 v94, v52, 0xc2080000, v76
	v_fmamk_f32 v95, v52, 0xc20c0000, v76
	v_fmamk_f32 v96, v52, 0xc2400000, v76
	v_fmamk_f32 v97, v52, 0xc2440000, v76
	v_fmamk_f32 v98, v52, 0xc2480000, v76
	v_fmamk_f32 v99, v52, 0xc24c0000, v76
	v_fmamk_f32 v113, v52, 0xc2800000, v76
	v_fmamk_f32 v115, v52, 0xc2820000, v76
	v_fmamk_f32 v117, v52, 0xc2840000, v76
	v_fmamk_f32 v119, v52, 0xc2860000, v76
	v_fmamk_f32 v121, v52, 0xc2a00000, v76
	v_fmamk_f32 v123, v52, 0xc2a20000, v76
	v_fmamk_f32 v124, v52, 0xc2a40000, v76
	v_fmamk_f32 v125, v52, 0xc2a60000, v76
	v_fmamk_f32 v126, v52, 0xc2c00000, v76
	v_fmamk_f32 v127, v52, 0xc2c20000, v76
	v_fmamk_f32 v128, v52, 0xc2c40000, v76
	v_fmamk_f32 v129, v52, 0xc2c60000, v76
	v_fmamk_f32 v130, v52, 0xc2e00000, v76
	v_fmamk_f32 v131, v52, 0xc2e20000, v76
	v_fmamk_f32 v132, v52, 0xc2e40000, v76
	v_fmac_f32_e32 v76, 0xc2e60000, v52
	v_mul_f32_e32 v85, 0x3fb8aa3b, v53
	v_xor_b32_e32 v53, 16, v235
	v_cmp_lt_i32_e32 vcc, v53, v3
	s_nop 1
	v_cndmask_b32_e32 v53, v235, v53, vcc
	v_lshlrev_b32_e32 v86, 2, v53
	v_xor_b32_e32 v53, 32, v235
	v_cmp_lt_i32_e32 vcc, v53, v3
	s_nop 1
	v_cndmask_b32_e32 v3, v235, v53, vcc
	v_lshlrev_b32_e32 v87, 2, v3
